# P2 two queues: 144 workgroups pull sample attention first, 112 pull prompt attention + conv first
# speedup vs baseline: 1.0329x; 1.0045x over previous
.LBB0_436:
	v_readlane_b32 s100, v248, 42
	s_mov_b32 s101, 0
	s_lshr_b32 s100, s100, 3
	s_and_b32 s100, s100, 15
	s_cmpk_lt_u32 s100, 9
	s_cselect_b32 s100, 1, 0
	s_load_dwordx4 s[28:31], s[52:53], 0x80
	s_waitcnt lgkmcnt(0)
	s_cmp_lt_i32 s30, 3
	s_cselect_b64 s[0:1], -1, 0
	s_and_b64 s[0:1], s[0:1], s[6:7]
	s_andn2_b64 vcc, exec, s[0:1]
	s_cbranch_vccnz .LBB0_610
	s_load_dwordx16 s[12:27], s[52:53], 0x0
	v_writelane_b32 v248, s0, 48
	v_mbcnt_lo_u32_b32 v3, -1, 0
	s_mov_b32 s11, 0x27000
	v_writelane_b32 v248, s1, 49
	s_waitcnt lgkmcnt(0)
	s_mov_b64 s[6:7], s[18:19]
	s_and_b32 s9, s7, 0xffff
	v_writelane_b32 v248, s33, 46
	s_add_u32 s0, s28, 0x2900000
	v_writelane_b32 v248, s0, 47
	s_addc_u32 s0, s29, 0
	v_writelane_b32 v248, s0, 44
	s_add_i32 s2, 0, 0x23200
	s_brev_b32 s10, -2
	s_mov_b32 s8, s18
	s_mov_b64 s[0:1], -1
	s_mov_b32 s21, 0
	v_mov_b32_e32 v2, 0
	v_writelane_b32 v248, s2, 38
	v_mov_b32_e32 v1, s2
	s_add_i32 s51, 0, 0x20000
	s_movk_i32 s33, 0x1000
	s_movk_i32 s50, 0x2000
	s_add_i32 s2, 0, 0x20800
	s_movk_i32 s19, 0x3000
	s_add_i32 s46, 0, 0x10000
	s_movk_i32 s6, 0x4000
	s_movk_i32 s17, 0x6000
	s_mov_b32 s31, 0x41000000
	s_movk_i32 s22, 0x5000
	s_movk_i32 s30, 0x7000
	v_mov_b32_e32 v204, 0x358637bd
	s_mov_b32 s18, 0xf800000
	v_mov_b32_e32 v205, 0x260
	v_mov_b32_e32 v196, 0xe0ad78ec
	v_mbcnt_hi_u32_b32 v206, -1, v3
	v_mov_b32_e32 v207, 3
	v_mov_b32_e32 v208, 2
	v_mov_b32_e32 v209, 1
	s_mov_b64 s[26:27], 0x100
	s_mov_b64 s[28:29], 0x1800
	s_mov_b64 s[34:35], 0x1900
	v_writelane_b32 v248, s2, 50
	s_branch .LBB0_440
